# grid barrier v2: arrivals counted per XCC (HW_REG_XCC_ID, census at the first sync); only the last-arriving workgroup of each XCC writes back its L2 and bumps the top counter
# speedup vs baseline: 1.2015x; 1.0779x over previous
; #define LAS __attribute__((address_space(3)))
; __global__ void __launch_bounds__(512, 2) mega_fwd(Args a_byval) {
;     extern __shared__ __attribute__((aligned(16))) unsigned char lds_raw[];
;     cg::grid_group grid = cg::this_grid();
;     const int ph_lo = a_byval.ph_lo, ph_hi = a_byval.ph_hi;
;     const int wave0 = __builtin_amdgcn_readfirstlane((int)threadIdx.x >> 6);
;     const int it_hi = ph_hi + (PROBE_DUP >= 0 ? 1 : 0);
;     for (int it = ph_lo; it < it_hi; ++it) {
;     const int ph = (PROBE_DUP >= 0 && it > PROBE_DUP) ? it - 1 : it;
;     const __attribute__((address_space(4))) unsigned char* kap = (const __attribute__((address_space(4))) unsigned char*)__builtin_amdgcn_kernarg_segment_ptr();
;     asm volatile("" : "+s"(kap));
;     const __attribute__((address_space(4))) Args& a = *(const __attribute__((address_space(4))) Args*)kap;
;     LAS unsigned char* lds = (LAS unsigned char*)lds_raw;
;     const int wave = wave0;
;     int G = gridDim.x, bx = blockIdx.x; asm volatile("" : "+s"(G), "+s"(bx));
;     const int vcu = (G % 8 == 0) ? (bx % 8) * (G / 8) + bx / 8 : bx;
;     const int gw = vcu * 8 + wave, NGW = G * 8;
;     const int gwm = wave * G + vcu;
.LBB0_1:
	s_mov_b32 s101, 0
	s_getreg_b32 s100, hwreg(HW_REG_XCC_ID)
	s_and_b32 s100, s100, 15
	s_lshl_b32 s100, s100, 8
	v_writelane_b32 v255, s100, 56
	s_mov_b32 s62, s2
	s_add_u32 s2, s58, 0xb0
	s_addc_u32 s3, s59, 0
	s_lshr_b32 s50, s0, 6
	v_writelane_b32 v255, s2, 0
	s_lshl_b32 s1, s50, 14
	s_load_dword s48, s[58:59], 0xb0
	v_writelane_b32 v255, s3, 1
	v_writelane_b32 v255, s1, 2
	s_add_i32 s56, s1, 0
	s_and_b32 s1, s0, 0xffffffc0
	s_lshl_b32 s2, s50, 7
	s_cmp_lg_u32 s2, 0x7fffff80
	s_cselect_b64 s[74:75], -1, 0
	s_ashr_i32 s3, s2, 31
	s_cmp_lt_u32 s0, 64
	v_writelane_b32 v255, s1, 3
	s_cselect_b64 s[60:61], -1, 0
	s_cmp_gt_u32 s0, 63
	v_writelane_b32 v255, s2, 4
	s_cselect_b64 s[84:85], -1, 0
	s_waitcnt lgkmcnt(0)
	s_cmpk_eq_i32 s48, 0x100
	v_writelane_b32 v255, s3, 5
	s_cselect_b64 s[0:1], -1, 0
	v_writelane_b32 v255, s0, 6
	v_lshrrev_b32_e32 v2, 20, v0
	v_lshrrev_b32_e32 v0, 10, v0
	v_writelane_b32 v255, s1, 7
	v_or_b32_e32 v0, v0, v2
	s_movk_i32 s0, 0x3ff
	v_and_or_b32 v0, v0, s0, v1
	v_cmp_eq_u32_e64 s[0:1], 0, v0
	s_mov_b32 s53, 0
	s_movk_i32 s57, 0x100
	v_writelane_b32 v255, s0, 8
	v_mov_b32_e32 v252, 0x358637bd
	s_mov_b32 s49, 0x800000
	v_writelane_b32 v255, s1, 9
	s_lshl_b32 s0, s50, 3
	s_or_b32 s0, s0, 4
	v_writelane_b32 v255, s0, 10
	v_writelane_b32 v255, s62, 11
	v_writelane_b32 v255, s58, 12
	s_movk_i32 s86, 0x1000
	v_mov_b32_e32 v129, 0
	v_writelane_b32 v255, s59, 13
	v_writelane_b32 v255, s48, 14
	v_writelane_b32 v255, s50, 15
	v_writelane_b32 v255, s56, 16
	v_writelane_b32 v255, s74, 17
	s_movk_i32 s41, 0x600
	s_movk_i32 s43, 0xff
	v_writelane_b32 v255, s75, 18
	v_writelane_b32 v255, s60, 19
	s_mov_b32 s63, 0x8400
	s_movk_i32 s94, 0xd0
	v_writelane_b32 v255, s61, 20
	v_writelane_b32 v255, s84, 21
	s_mov_b32 s33, 0x41000000
	s_movk_i32 s77, 0x5800
	s_mov_b32 s78, 0x10000
	s_mov_b32 s79, 0x30000
	s_mov_b32 s76, 0x18000
	s_mov_b32 s51, 0x500000
	s_movk_i32 s1, 0x1600
	v_mov_b64_e32 v[238:239], 0x100
	s_mov_b64 s[54:55], 0x80
	v_writelane_b32 v255, s85, 22
	s_branch .LBB0_5

; __device__ __forceinline__ unsigned cvt_pk_bf16(float lo, float hi) { const f32x2 v = {lo, hi}; return __builtin_bit_cast(unsigned, __builtin_convertvector(v, bf16x2_t)); }
; __device__ __forceinline__ float fast_silu(float g) { return g * __builtin_amdgcn_rcpf(1.0f + __builtin_amdgcn_exp2f(-1.4426950408889634f * g)); }
; __device__ __forceinline__ float sum4(f32x4 v) { return (v.x + v.y) + (v.z + v.w); }
; __device__ __forceinline__ float quad_sum(float t, int lane) { t += shx(t, 16, lane); t += shx(t, 32, lane); return t; }
;     template <int A0, int A1> __device__ __forceinline__ void run(const f32x4 (&acc)[2][2][4][2], const Unit& u, int wr, int wc, int fr, int fq) const {
;     ...
; #pragma unroll
;         for (int ai = A0; ai < A1; ++ai)
; #pragma unroll
;             for (int m = 0; m < 4; ++m) {
;                 const int row = row0 + ai * 128 + m * 16;
;                 const float t = quad_sum(sum4(*(const f32x4*)(ssqp + (size_t)row * 16 + 4 * fq)), fq * 16 + fr);
;                 const float rr = rsqrtf(t * (1.0f / 1024.0f) + EPS);
;                 u32x4 w;
; #pragma unroll
;                 for (int n = 0; n < 2; ++n) {
;                     const f32x4 gg = acc[ai][0][m][n] * rr + bg[n], uu = acc[ai][1][m][n] * rr + bu[n];
;                     const float h0 = fast_silu(gg.x) * uu.x, h1 = fast_silu(gg.y) * uu.y, h2 = fast_silu(gg.z) * uu.z, h3 = fast_silu(gg.w) * uu.w;
;                     w[2 * n] = cvt_pk_bf16(h0, h1); w[2 * n + 1] = cvt_pk_bf16(h2, h3);
;                 }
;                 bf16_t* hp = H + (size_t)row * DFF + u.pn * 128 + wc * 32 + fq * 8;
;                 if (cnt) asm volatile("global_store_dwordx4 %0, %1, off sc0 sc1" :: "v"(hp), "v"(w) : "memory");
;                 else *(u32x4*)hp = w;
.LBB0_238:
	v_or_b32_e32 v130, 16, v160
	v_ashrrev_i32_e32 v131, 31, v130
	v_mov_b64_e32 v[132:133], v[224:225]
	v_mov_b64_e32 v[134:135], v[226:227]
	global_load_dwordx4 v[224:227], v[236:237], off offset:3072
	v_mov_b32_e32 v136, v133
	v_mov_b32_e32 v137, v134
	v_mov_b32_e32 v133, v135
	v_pk_add_f32 v[132:133], v[136:137], v[132:133]
	s_nop 0
	v_add_f32_e32 v131, v132, v133
	ds_bpermute_b32 v132, v164, v131
	s_waitcnt lgkmcnt(0)
	v_add_f32_e32 v131, v131, v132
	ds_bpermute_b32 v132, v165, v131
	s_waitcnt lgkmcnt(0)
	v_add_f32_e32 v131, v131, v132
	v_fmamk_f32 v131, v131, 0x3a800000, v252
	v_cmp_gt_f32_e32 vcc, s49, v131
	v_mul_f32_e32 v132, 0x4b800000, v131
	s_nop 0
	v_cndmask_b32_e32 v131, v131, v132, vcc
	v_rsq_f32_e32 v131, v131
	s_nop 0
	v_mul_f32_e32 v132, 0x45800000, v131
	v_cndmask_b32_e32 v132, v131, v132, vcc
	v_pk_fma_f32 v[124:125], v[124:125], v[132:133], v[44:45] op_sel_hi:[1,0,1]
	v_pk_fma_f32 v[126:127], v[126:127], v[132:133], v[46:47] op_sel_hi:[1,0,1]
	v_mul_f32_e32 v131, 0xbfb8aa3b, v124
	v_exp_f32_e32 v131, v131
	v_pk_fma_f32 v[116:117], v[116:117], v[132:133], v[40:41] op_sel_hi:[1,0,1]
	v_pk_fma_f32 v[118:119], v[118:119], v[132:133], v[42:43] op_sel_hi:[1,0,1]
	v_pk_fma_f32 v[120:121], v[120:121], v[132:133], v[36:37] op_sel_hi:[1,0,1]
	v_add_f32_e32 v131, 1.0, v131
	v_rcp_f32_e32 v134, v131
	v_mul_f32_e32 v131, 0xbfb8aa3b, v125
	v_exp_f32_e32 v131, v131
	v_pk_fma_f32 v[112:113], v[112:113], v[132:133], v[32:33] op_sel_hi:[1,0,1]
	v_pk_fma_f32 v[114:115], v[114:115], v[132:133], v[34:35] op_sel_hi:[1,0,1]
	s_and_b64 vcc, exec, s[6:7]
	v_add_f32_e32 v131, 1.0, v131
	v_rcp_f32_e32 v135, v131
	s_nop 0
	v_pk_mul_f32 v[124:125], v[124:125], v[134:135]
	s_nop 0
	v_pk_mul_f32 v[116:117], v[116:117], v[124:125]
	v_mul_f32_e32 v124, 0xbfb8aa3b, v126
	v_mul_f32_e32 v125, 0xbfb8aa3b, v127
	v_exp_f32_e32 v124, v124
	v_exp_f32_e32 v125, v125
	v_cvt_pk_bf16_f32 v116, v116, v117
	v_add_f32_e32 v124, 1.0, v124
	v_add_f32_e32 v125, 1.0, v125
	v_rcp_f32_e32 v124, v124
	v_rcp_f32_e32 v125, v125
	s_nop 0
	v_pk_mul_f32 v[124:125], v[126:127], v[124:125]
	s_nop 0
	v_pk_mul_f32 v[118:119], v[118:119], v[124:125]
	s_nop 0
	v_cvt_pk_bf16_f32 v117, v118, v119
	v_pk_fma_f32 v[118:119], v[122:123], v[132:133], v[38:39] op_sel_hi:[1,0,1]
	v_mul_f32_e32 v122, 0xbfb8aa3b, v120
	v_mul_f32_e32 v123, 0xbfb8aa3b, v121
	v_exp_f32_e32 v122, v122
	v_exp_f32_e32 v123, v123
	v_add_f32_e32 v122, 1.0, v122
	v_add_f32_e32 v123, 1.0, v123
	v_rcp_f32_e32 v122, v122
	v_rcp_f32_e32 v123, v123
	s_nop 0
	v_pk_mul_f32 v[120:121], v[120:121], v[122:123]
	s_nop 0
	v_pk_mul_f32 v[112:113], v[112:113], v[120:121]
	v_mul_f32_e32 v120, 0xbfb8aa3b, v118
	v_mul_f32_e32 v121, 0xbfb8aa3b, v119
	v_exp_f32_e32 v120, v120
	v_exp_f32_e32 v121, v121
	v_add_f32_e32 v120, 1.0, v120
	v_add_f32_e32 v121, 1.0, v121
	v_rcp_f32_e32 v120, v120
	v_rcp_f32_e32 v121, v121
	s_nop 0
	v_pk_mul_f32 v[118:119], v[118:119], v[120:121]
	s_nop 0
	v_pk_mul_f32 v[114:115], v[114:115], v[118:119]
	v_cvt_pk_bf16_f32 v118, v112, v113
	v_mov_b64_e32 v[112:113], s[12:13]
	v_mad_i64_i32 v[112:113], s[20:21], v130, s1, v[112:113]
	v_lshl_add_u64 v[112:113], s[84:85], 1, v[112:113]
	v_lshl_add_u64 v[112:113], v[112:113], 0, s[52:53]
	v_cvt_pk_bf16_f32 v119, v114, v115
	v_lshl_add_u64 v[112:113], v[112:113], 0, v[128:129]
	s_cbranch_vccnz .LBB0_268
	global_store_dwordx4 v[112:113], v[116:119], off sc0 sc1
	s_cbranch_execnz .LBB0_241

; __device__ __forceinline__ unsigned cvt_pk_bf16(float lo, float hi) { const f32x2 v = {lo, hi}; return __builtin_bit_cast(unsigned, __builtin_convertvector(v, bf16x2_t)); }
; __device__ __forceinline__ float fast_silu(float g) { return g * __builtin_amdgcn_rcpf(1.0f + __builtin_amdgcn_exp2f(-1.4426950408889634f * g)); }
; __device__ __forceinline__ float sum4(f32x4 v) { return (v.x + v.y) + (v.z + v.w); }
; __device__ __forceinline__ float quad_sum(float t, int lane) { t += shx(t, 16, lane); t += shx(t, 32, lane); return t; }
;     template <int A0, int A1> __device__ __forceinline__ void run(const f32x4 (&acc)[2][2][4][2], const Unit& u, int wr, int wc, int fr, int fq) const {
;     ...
; #pragma unroll
;         for (int ai = A0; ai < A1; ++ai)
; #pragma unroll
;             for (int m = 0; m < 4; ++m) {
;                 const int row = row0 + ai * 128 + m * 16;
;                 const float t = quad_sum(sum4(*(const f32x4*)(ssqp + (size_t)row * 16 + 4 * fq)), fq * 16 + fr);
;                 const float rr = rsqrtf(t * (1.0f / 1024.0f) + EPS);
;                 u32x4 w;
; #pragma unroll
;                 for (int n = 0; n < 2; ++n) {
;                     const f32x4 gg = acc[ai][0][m][n] * rr + bg[n], uu = acc[ai][1][m][n] * rr + bu[n];
;                     const float h0 = fast_silu(gg.x) * uu.x, h1 = fast_silu(gg.y) * uu.y, h2 = fast_silu(gg.z) * uu.z, h3 = fast_silu(gg.w) * uu.w;
;                     w[2 * n] = cvt_pk_bf16(h0, h1); w[2 * n + 1] = cvt_pk_bf16(h2, h3);
;                 }
;                 bf16_t* hp = H + (size_t)row * DFF + u.pn * 128 + wc * 32 + fq * 8;
;                 if (cnt) asm volatile("global_store_dwordx4 %0, %1, off sc0 sc1" :: "v"(hp), "v"(w) : "memory");
;                 else *(u32x4*)hp = w;
.LBB0_256:
	v_add_u32_e32 v16, 0xb0, v160
	v_ashrrev_i32_e32 v17, 31, v16
	s_waitcnt vmcnt(6)
	v_mov_b64_e32 v[18:19], v[224:225]
	v_mov_b64_e32 v[20:21], v[226:227]
	v_mov_b32_e32 v22, v19
	v_mov_b32_e32 v23, v20
	v_mov_b32_e32 v19, v21
	v_pk_add_f32 v[18:19], v[22:23], v[18:19]
	s_nop 0
	v_add_f32_e32 v17, v18, v19
	ds_bpermute_b32 v18, v164, v17
	s_waitcnt lgkmcnt(0)
	v_add_f32_e32 v17, v17, v18
	ds_bpermute_b32 v18, v165, v17
	s_waitcnt lgkmcnt(0)
	v_add_f32_e32 v17, v17, v18
	v_fmamk_f32 v17, v17, 0x3a800000, v252
	v_cmp_gt_f32_e32 vcc, s49, v17
	v_mul_f32_e32 v18, 0x4b800000, v17
	s_nop 0
	v_cndmask_b32_e32 v17, v17, v18, vcc
	v_rsq_f32_e32 v17, v17
	s_nop 0
	v_mul_f32_e32 v18, 0x45800000, v17
	v_cndmask_b32_e32 v18, v17, v18, vcc
	v_pk_fma_f32 v[12:13], v[12:13], v[18:19], v[44:45] op_sel_hi:[1,0,1]
	v_pk_fma_f32 v[14:15], v[14:15], v[18:19], v[46:47] op_sel_hi:[1,0,1]
	v_mul_f32_e32 v17, 0xbfb8aa3b, v12
	v_exp_f32_e32 v17, v17
	v_pk_fma_f32 v[4:5], v[4:5], v[18:19], v[40:41] op_sel_hi:[1,0,1]
	v_pk_fma_f32 v[6:7], v[6:7], v[18:19], v[42:43] op_sel_hi:[1,0,1]
	v_pk_fma_f32 v[8:9], v[8:9], v[18:19], v[36:37] op_sel_hi:[1,0,1]
	v_add_f32_e32 v17, 1.0, v17
	v_rcp_f32_e32 v20, v17
	v_mul_f32_e32 v17, 0xbfb8aa3b, v13
	v_exp_f32_e32 v17, v17
	v_pk_fma_f32 v[0:1], v[0:1], v[18:19], v[32:33] op_sel_hi:[1,0,1]
	v_pk_fma_f32 v[2:3], v[2:3], v[18:19], v[34:35] op_sel_hi:[1,0,1]
	s_and_b64 vcc, exec, s[6:7]
	v_add_f32_e32 v17, 1.0, v17
	v_rcp_f32_e32 v21, v17
	s_nop 0
	v_pk_mul_f32 v[12:13], v[12:13], v[20:21]
	s_nop 0
	v_pk_mul_f32 v[4:5], v[4:5], v[12:13]
	v_mul_f32_e32 v12, 0xbfb8aa3b, v14
	v_mul_f32_e32 v13, 0xbfb8aa3b, v15
	v_exp_f32_e32 v12, v12
	v_exp_f32_e32 v13, v13
	v_cvt_pk_bf16_f32 v4, v4, v5
	v_add_f32_e32 v12, 1.0, v12
	v_add_f32_e32 v13, 1.0, v13
	v_rcp_f32_e32 v12, v12
	v_rcp_f32_e32 v13, v13
	s_nop 0
	v_pk_mul_f32 v[12:13], v[14:15], v[12:13]
	s_nop 0
	v_pk_mul_f32 v[6:7], v[6:7], v[12:13]
	s_nop 0
	v_cvt_pk_bf16_f32 v5, v6, v7
	v_pk_fma_f32 v[6:7], v[10:11], v[18:19], v[38:39] op_sel_hi:[1,0,1]
	v_mul_f32_e32 v10, 0xbfb8aa3b, v8
	v_mul_f32_e32 v11, 0xbfb8aa3b, v9
	v_exp_f32_e32 v10, v10
	v_exp_f32_e32 v11, v11
	v_add_f32_e32 v10, 1.0, v10
	v_add_f32_e32 v11, 1.0, v11
	v_rcp_f32_e32 v10, v10
	v_rcp_f32_e32 v11, v11
	s_nop 0
	v_pk_mul_f32 v[8:9], v[8:9], v[10:11]
	s_nop 0
	v_pk_mul_f32 v[0:1], v[0:1], v[8:9]
	v_mul_f32_e32 v8, 0xbfb8aa3b, v6
	v_mul_f32_e32 v9, 0xbfb8aa3b, v7
	v_exp_f32_e32 v8, v8
	v_exp_f32_e32 v9, v9
	v_add_f32_e32 v8, 1.0, v8
	v_add_f32_e32 v9, 1.0, v9
	v_rcp_f32_e32 v8, v8
	v_rcp_f32_e32 v9, v9
	s_nop 0
	v_pk_mul_f32 v[6:7], v[6:7], v[8:9]
	s_nop 0
	v_pk_mul_f32 v[2:3], v[2:3], v[6:7]
	v_cvt_pk_bf16_f32 v6, v0, v1
	v_mov_b64_e32 v[0:1], s[12:13]
	v_mad_i64_i32 v[0:1], s[20:21], v16, s1, v[0:1]
	v_lshl_add_u64 v[0:1], s[84:85], 1, v[0:1]
	v_lshl_add_u64 v[0:1], v[0:1], 0, s[52:53]
	v_cvt_pk_bf16_f32 v7, v2, v3
	v_lshl_add_u64 v[0:1], v[0:1], 0, v[128:129]
	s_cbranch_vccnz .LBB0_274
	global_store_dwordx4 v[0:1], v[4:7], off sc0 sc1
	s_cbranch_execnz .LBB0_259

; __global__ void __launch_bounds__(512, 2) mega_fwd(Args a_byval) {
;     ...
;         { const bool ffn_in_seam = (ph >= 2 && ph < 18 && (((ph - 2) & 7) == 0 || ((ph - 2) & 7) == 6)) && (int)gridDim.x == 256;
;           if (it + 1 < it_hi && !ffn_in_seam) grid.sync(); }
.LBB0_1499:
	v_readlane_b32 s6, v255, 12
	v_readlane_b32 s7, v255, 13
	s_add_i32 s101, s101, 1
	s_load_dwordx2 s[6:7], s[6:7], 0xa0
	v_readlane_b32 s8, v255, 56
	v_mov_b32_e32 v2, 1
	s_waitcnt lgkmcnt(0)
	s_add_u32 s6, s6, 0x3a000
	s_addc_u32 s7, s7, 0
	v_mov_b32_e32 v0, s8
	s_cmp_lg_u32 s101, 1
	s_cbranch_scc1 .Lgh_hier
	s_add_u32 s12, s6, 0x1100
	s_addc_u32 s13, s7, 0
	global_atomic_add v1, v0, v2, s[12:13] sc0
	buffer_wbl2 sc1
	s_waitcnt vmcnt(0)
	global_atomic_add v129, v2, s[6:7]
	v_readlane_b32 s0, v255, 14
.Lgh_spin1:
	s_sleep 1
	global_load_dword v1, v129, s[6:7] sc1
	s_waitcnt vmcnt(0)
	v_cmp_gt_u32_e32 vcc, s0, v1
	s_cbranch_vccnz .Lgh_spin1
	s_mov_b32 s9, 0
	s_mov_b32 s10, 0
	s_mov_b32 s2, 0
.Lgh_cens:
	v_mov_b32_e32 v0, s10
	s_nop 0
	global_load_dword v1, v0, s[12:13] sc1
	s_waitcnt vmcnt(0)
	v_readfirstlane_b32 s11, v1
	s_nop 0
	s_cmp_lg_u32 s11, 0
	s_cselect_b32 s3, 1, 0
	s_add_i32 s9, s9, s3
	s_cmp_eq_u32 s10, s8
	s_cselect_b32 s2, s11, s2
	s_addk_i32 s10, 0x100
	s_cmp_lt_u32 s10, 0x1000
	s_cbranch_scc1 .Lgh_cens
	v_writelane_b32 v255, s2, 57
	v_writelane_b32 v255, s9, 58
	s_branch .Lgh_done
.Lgh_hier:
	v_readlane_b32 s2, v255, 57
	v_readlane_b32 s9, v255, 58
	s_add_i32 s10, s101, -1
	s_add_u32 s12, s6, 0x100
	s_addc_u32 s13, s7, 0
	s_mul_i32 s11, s10, s2
	s_mul_i32 s3, s10, s9
	global_atomic_add v1, v0, v2, s[12:13] sc0
	s_waitcnt vmcnt(0)
	v_readfirstlane_b32 s0, v1
	s_nop 0
	s_add_i32 s0, s0, 1
	s_cmp_lg_u32 s0, s11
	s_cbranch_scc1 .Lgh_wait
	buffer_wbl2 sc1
	s_waitcnt vmcnt(0)
	global_atomic_add v129, v2, s[6:7] offset:64
.Lgh_wait:
	s_sleep 1
	global_load_dword v1, v129, s[6:7] offset:64 sc1
	s_waitcnt vmcnt(0)
	v_cmp_gt_u32_e32 vcc, s3, v1
	s_cbranch_vccnz .Lgh_wait
